# P5 tile epilogue: wait for second row-group's residual loads before the first group's stores (no store drain)
# speedup vs baseline: 1.0084x; 1.0022x over previous
.LBB0_624:
	s_or_b64 exec, exec, s[4:5]
	v_readlane_b32 s80, v242, 21
	v_readlane_b32 s81, v242, 22
	v_or_b32_e32 v116, 32, v150
	v_readlane_b32 s82, v242, 23
	v_readlane_b32 s83, v242, 24
	s_mov_b64 s[36:37], s[80:81]
	v_add_u32_e32 v98, 0xffffc020, v150
	v_ashrrev_i32_e32 v117, 31, v116
	v_cmp_gt_i32_e64 s[4:5], s45, v116
	s_mov_b64 s[38:39], s[82:83]
	v_mov_b32_e32 v102, s39
	s_waitcnt lgkmcnt(0)
	v_cndmask_b32_e64 v99, 0, v117, s[4:5]
	v_cndmask_b32_e64 v98, v98, v116, s[4:5]
	v_mov_b32_e32 v103, s37
	v_mov_b32_e32 v104, s38
	v_mov_b32_e32 v105, s36
	v_cndmask_b32_e64 v101, v102, v103, s[4:5]
	v_cndmask_b32_e64 v100, v104, v105, s[4:5]
	v_lshlrev_b64 v[98:99], 12, v[98:99]
	v_lshl_add_u64 v[98:99], v[100:101], 0, v[98:99]
	v_lshl_add_u64 v[98:99], v[98:99], 0, v[152:153]
	global_load_dwordx4 v[118:121], v[98:99], off
	global_load_dwordx4 v[124:127], v[98:99], off offset:16
	global_load_dwordx4 v[128:131], v[98:99], off offset:512
	global_load_dwordx4 v[132:135], v[98:99], off offset:528
	v_or_b32_e32 v114, 48, v150
	v_add_u32_e32 v98, 0xffffc030, v150
	v_ashrrev_i32_e32 v115, 31, v114
	v_cmp_gt_i32_e64 s[4:5], s45, v114
	v_readlane_b32 s84, v242, 25
	v_readlane_b32 s85, v242, 26
	v_cndmask_b32_e64 v99, 0, v115, s[4:5]
	v_cndmask_b32_e64 v98, v98, v114, s[4:5]
	v_cndmask_b32_e64 v101, v102, v103, s[4:5]
	v_cndmask_b32_e64 v100, v104, v105, s[4:5]
	v_lshlrev_b64 v[98:99], 12, v[98:99]
	v_lshl_add_u64 v[98:99], v[100:101], 0, v[98:99]
	v_lshl_add_u64 v[102:103], v[98:99], 0, v[152:153]
	global_load_dwordx4 v[106:109], v[102:103], off offset:16
	global_load_dwordx4 v[110:113], v[102:103], off
	global_load_dwordx4 v[98:101], v[102:103], off offset:528
	s_nop 0
	global_load_dwordx4 v[102:105], v[102:103], off offset:512
	v_readlane_b32 s86, v242, 27
	v_readlane_b32 s87, v242, 28
	v_readlane_b32 s88, v242, 29
	v_readlane_b32 s89, v242, 30
	v_readlane_b32 s90, v242, 31
	v_readlane_b32 s91, v242, 32
	v_readlane_b32 s92, v242, 33
	v_readlane_b32 s93, v242, 34
	v_readlane_b32 s94, v242, 35
	v_readlane_b32 s95, v242, 36
	s_waitcnt vmcnt(7)
	v_pk_add_f32 v[96:97], v[96:97], v[120:121]
	v_pk_add_f32 v[94:95], v[94:95], v[118:119]
	s_waitcnt vmcnt(6)
	v_pk_add_f32 v[92:93], v[92:93], v[126:127]
	v_pk_add_f32 v[90:91], v[90:91], v[124:125]
	s_waitcnt vmcnt(5)
	v_pk_add_f32 v[118:119], v[88:89], v[130:131]
	v_pk_add_f32 v[88:89], v[86:87], v[128:129]
	s_waitcnt vmcnt(4)
	v_pk_add_f32 v[120:121], v[84:85], v[134:135]
	v_pk_add_f32 v[82:83], v[82:83], v[132:133]
	v_cvt_pk_bf16_f32 v84, v94, v95
	v_cvt_pk_bf16_f32 v85, v96, v97
	v_cvt_pk_bf16_f32 v86, v90, v91
	v_cvt_pk_bf16_f32 v87, v92, v93
	v_cvt_pk_bf16_f32 v88, v88, v89
	v_cvt_pk_bf16_f32 v89, v118, v119
	s_nop 0
	v_cvt_pk_bf16_f32 v90, v82, v83
	v_cvt_pk_bf16_f32 v91, v120, v121
	v_and_b32_e32 v83, 0xffff0000, v84
	v_and_b32_e32 v93, 0xffff0000, v85
	v_and_b32_e32 v95, 0xffff0000, v86
	v_and_b32_e32 v97, 0xffff0000, v87
	v_and_b32_e32 v119, 0xffff0000, v88
	v_and_b32_e32 v121, 0xffff0000, v89
	v_and_b32_e32 v125, 0xffff0000, v90
	v_and_b32_e32 v127, 0xffff0000, v91
	v_lshlrev_b32_e32 v82, 16, v84
	v_lshlrev_b32_e32 v92, 16, v85
	v_lshlrev_b32_e32 v94, 16, v86
	v_lshlrev_b32_e32 v96, 16, v87
	v_lshlrev_b32_e32 v118, 16, v88
	v_lshlrev_b32_e32 v120, 16, v89
	v_lshlrev_b32_e32 v124, 16, v90
	v_lshlrev_b32_e32 v126, 16, v91
	v_mul_f32_e32 v83, v83, v83
	v_mul_f32_e32 v93, v93, v93
	v_mul_f32_e32 v95, v95, v95
	v_mul_f32_e32 v97, v97, v97
	v_mul_f32_e32 v119, v119, v119
	v_mul_f32_e32 v121, v121, v121
	v_mul_f32_e32 v125, v125, v125
	v_mul_f32_e32 v127, v127, v127
	v_fmac_f32_e32 v83, v82, v82
	v_fmac_f32_e32 v93, v92, v92
	v_fmac_f32_e32 v95, v94, v94
	v_fmac_f32_e32 v97, v96, v96
	v_fmac_f32_e32 v119, v118, v118
	v_fmac_f32_e32 v121, v120, v120
	v_fmac_f32_e32 v125, v124, v124
	v_fmac_f32_e32 v127, v126, v126
	v_add_f32_e32 v82, v83, v93
	v_add_f32_e32 v83, v95, v97
	v_add_f32_e32 v92, v119, v121
	v_add_f32_e32 v93, v125, v127
	v_add_f32_e32 v82, v82, v83
	v_add_f32_e32 v83, v92, v93
	v_add_f32_e32 v82, v82, v83
	ds_bpermute_b32 v83, v122, v82
	v_lshlrev_b64 v[92:93], 11, v[116:117]
	v_lshl_add_u64 v[92:93], s[2:3], 0, v[92:93]
	v_lshl_add_u64 v[92:93], v[148:149], 1, v[92:93]
	s_waitcnt vmcnt(0)
	global_store_dwordx4 v[92:93], v[84:87], off
	global_store_dwordx4 v[92:93], v[88:91], off offset:256
	s_waitcnt lgkmcnt(0)
	v_add_f32_e32 v82, v82, v83
	ds_bpermute_b32 v83, v123, v82
	s_and_saveexec_b64 s[4:5], vcc
	s_cbranch_execz .LBB0_626
	v_lshlrev_b64 v[84:85], 6, v[116:117]
	v_lshl_add_u64 v[84:85], s[8:9], 0, v[84:85]
	s_lshl_b32 s12, s34, 2
	v_lshl_add_u64 v[84:85], v[84:85], 0, s[12:13]
	s_waitcnt lgkmcnt(0)
	v_add_f32_e32 v82, v82, v83
	global_store_dword v[84:85], v82, off
.LBB0_626:
	s_or_b64 exec, exec, s[4:5]
	v_pk_add_f32 v[78:79], v[78:79], v[110:111]
	v_pk_add_f32 v[80:81], v[80:81], v[112:113]
	s_waitcnt lgkmcnt(0)
	v_pk_add_f32 v[82:83], v[76:77], v[108:109]
	v_pk_add_f32 v[76:77], v[74:75], v[106:107]
	v_cvt_pk_bf16_f32 v74, v78, v79
	v_cvt_pk_bf16_f32 v75, v80, v81
	v_pk_add_f32 v[70:71], v[70:71], v[102:103]
	v_and_b32_e32 v79, 0xffff0000, v74
	v_lshlrev_b32_e32 v78, 16, v74
	v_and_b32_e32 v81, 0xffff0000, v75
	v_mul_f32_e32 v79, v79, v79
	v_lshlrev_b32_e32 v80, 16, v75
	v_fmac_f32_e32 v79, v78, v78
	v_mul_f32_e32 v78, v81, v81
	v_cvt_pk_bf16_f32 v76, v76, v77
	v_cvt_pk_bf16_f32 v77, v82, v83
	v_fmac_f32_e32 v78, v80, v80
	v_and_b32_e32 v83, 0xffff0000, v76
	v_and_b32_e32 v85, 0xffff0000, v77
	v_lshlrev_b32_e32 v82, 16, v76
	v_lshlrev_b32_e32 v84, 16, v77
	v_add_f32_e32 v78, v79, v78
	v_mul_f32_e32 v79, v83, v83
	v_mul_f32_e32 v80, v85, v85
	v_fmac_f32_e32 v79, v82, v82
	v_fmac_f32_e32 v80, v84, v84
	v_add_f32_e32 v79, v79, v80
	v_pk_add_f32 v[66:67], v[66:67], v[98:99]
	v_add_f32_e32 v80, v78, v79
	v_pk_add_f32 v[72:73], v[72:73], v[104:105]
	v_pk_add_f32 v[78:79], v[68:69], v[100:101]
	v_cvt_pk_bf16_f32 v68, v70, v71
	v_cvt_pk_bf16_f32 v70, v66, v67
	v_cvt_pk_bf16_f32 v69, v72, v73
	s_nop 0
	v_and_b32_e32 v67, 0xffff0000, v68
	v_lshlrev_b32_e32 v66, 16, v68
	v_and_b32_e32 v73, 0xffff0000, v69
	v_mul_f32_e32 v67, v67, v67
	v_lshlrev_b32_e32 v72, 16, v69
	v_fmac_f32_e32 v67, v66, v66
	v_mul_f32_e32 v66, v73, v73
	v_cvt_pk_bf16_f32 v71, v78, v79
	v_and_b32_e32 v79, 0xffff0000, v70
	v_and_b32_e32 v82, 0xffff0000, v71
	v_fmac_f32_e32 v66, v72, v72
	v_lshlrev_b32_e32 v78, 16, v70
	v_lshlrev_b32_e32 v81, 16, v71
	v_add_f32_e32 v66, v67, v66
	v_mul_f32_e32 v67, v79, v79
	v_mul_f32_e32 v72, v82, v82
	v_fmac_f32_e32 v67, v78, v78
	v_fmac_f32_e32 v72, v81, v81
	v_add_f32_e32 v67, v67, v72
	v_add_f32_e32 v66, v66, v67
	v_add_f32_e32 v66, v80, v66
	ds_bpermute_b32 v67, v122, v66
	v_lshlrev_b64 v[72:73], 11, v[114:115]
	v_lshl_add_u64 v[72:73], s[2:3], 0, v[72:73]
	v_lshl_add_u64 v[72:73], v[148:149], 1, v[72:73]
	global_store_dwordx4 v[72:73], v[74:77], off
	global_store_dwordx4 v[72:73], v[68:71], off offset:256
	s_waitcnt lgkmcnt(0)
	v_add_f32_e32 v66, v66, v67
	ds_bpermute_b32 v67, v123, v66
	s_and_saveexec_b64 s[4:5], vcc
	s_cbranch_execz .LBB0_628
	v_lshlrev_b64 v[68:69], 6, v[114:115]
	v_lshl_add_u64 v[68:69], s[8:9], 0, v[68:69]
	s_lshl_b32 s12, s34, 2
	v_lshl_add_u64 v[68:69], v[68:69], 0, s[12:13]
	s_waitcnt lgkmcnt(0)
	v_add_f32_e32 v66, v66, v67
	global_store_dword v[68:69], v66, off
.LBB0_628:
	s_or_b64 exec, exec, s[4:5]
	v_readlane_b32 s80, v242, 21
	v_readlane_b32 s81, v242, 22
	v_add_u32_e32 v84, 0x80, v150
	v_readlane_b32 s82, v242, 23
	v_readlane_b32 s83, v242, 24
	s_mov_b64 s[36:37], s[80:81]
	v_add_u32_e32 v66, 0xffffc080, v150
	v_ashrrev_i32_e32 v85, 31, v84
	v_cmp_gt_i32_e64 s[4:5], s45, v84
	s_mov_b64 s[38:39], s[82:83]
	v_mov_b32_e32 v70, s39
	s_waitcnt lgkmcnt(0)
	v_cndmask_b32_e64 v67, 0, v85, s[4:5]
	v_cndmask_b32_e64 v66, v66, v84, s[4:5]
	v_mov_b32_e32 v71, s37
	v_mov_b32_e32 v72, s38
	v_mov_b32_e32 v73, s36
	v_cndmask_b32_e64 v69, v70, v71, s[4:5]
	v_cndmask_b32_e64 v68, v72, v73, s[4:5]
	v_lshlrev_b64 v[66:67], 12, v[66:67]
	v_lshl_add_u64 v[66:67], v[68:69], 0, v[66:67]
	v_lshl_add_u64 v[66:67], v[66:67], 0, v[152:153]
	global_load_dwordx4 v[86:89], v[66:67], off
	global_load_dwordx4 v[90:93], v[66:67], off offset:16
	global_load_dwordx4 v[94:97], v[66:67], off offset:512
	global_load_dwordx4 v[98:101], v[66:67], off offset:528
	v_add_u32_e32 v82, 0x90, v150
	v_add_u32_e32 v66, 0xffffc090, v150
	v_ashrrev_i32_e32 v83, 31, v82
	v_cmp_gt_i32_e64 s[4:5], s45, v82
	v_readlane_b32 s84, v242, 25
	v_readlane_b32 s85, v242, 26
	v_cndmask_b32_e64 v67, 0, v83, s[4:5]
	v_cndmask_b32_e64 v66, v66, v82, s[4:5]
	v_cndmask_b32_e64 v69, v70, v71, s[4:5]
	v_cndmask_b32_e64 v68, v72, v73, s[4:5]
	v_lshlrev_b64 v[66:67], 12, v[66:67]
	v_lshl_add_u64 v[66:67], v[68:69], 0, v[66:67]
	v_lshl_add_u64 v[70:71], v[66:67], 0, v[152:153]
	global_load_dwordx4 v[74:77], v[70:71], off offset:16
	global_load_dwordx4 v[78:81], v[70:71], off
	global_load_dwordx4 v[66:69], v[70:71], off offset:528
	s_nop 0
	global_load_dwordx4 v[70:73], v[70:71], off offset:512
	v_readlane_b32 s86, v242, 27
	v_readlane_b32 s87, v242, 28
	v_readlane_b32 s88, v242, 29
	v_readlane_b32 s89, v242, 30
	v_readlane_b32 s90, v242, 31
	v_readlane_b32 s91, v242, 32
	v_readlane_b32 s92, v242, 33
	v_readlane_b32 s93, v242, 34
	v_readlane_b32 s94, v242, 35
	v_readlane_b32 s95, v242, 36
	s_waitcnt vmcnt(7)
	v_pk_add_f32 v[64:65], v[64:65], v[88:89]
	v_pk_add_f32 v[62:63], v[62:63], v[86:87]
	s_waitcnt vmcnt(6)
	v_pk_add_f32 v[60:61], v[60:61], v[92:93]
	v_pk_add_f32 v[58:59], v[58:59], v[90:91]
	s_waitcnt vmcnt(5)
	v_pk_add_f32 v[86:87], v[56:57], v[96:97]
	v_pk_add_f32 v[56:57], v[54:55], v[94:95]
	s_waitcnt vmcnt(4)
	v_pk_add_f32 v[88:89], v[52:53], v[100:101]
	v_pk_add_f32 v[50:51], v[50:51], v[98:99]
	v_cvt_pk_bf16_f32 v52, v62, v63
	v_cvt_pk_bf16_f32 v53, v64, v65
	v_cvt_pk_bf16_f32 v54, v58, v59
	v_cvt_pk_bf16_f32 v55, v60, v61
	v_cvt_pk_bf16_f32 v56, v56, v57
	v_cvt_pk_bf16_f32 v57, v86, v87
	s_nop 0
	v_cvt_pk_bf16_f32 v58, v50, v51
	v_cvt_pk_bf16_f32 v59, v88, v89
	v_and_b32_e32 v51, 0xffff0000, v52
	v_and_b32_e32 v61, 0xffff0000, v53
	v_and_b32_e32 v63, 0xffff0000, v54
	v_and_b32_e32 v65, 0xffff0000, v55
	v_and_b32_e32 v87, 0xffff0000, v56
	v_and_b32_e32 v89, 0xffff0000, v57
	v_and_b32_e32 v91, 0xffff0000, v58
	v_and_b32_e32 v93, 0xffff0000, v59
	v_lshlrev_b32_e32 v50, 16, v52
	v_lshlrev_b32_e32 v60, 16, v53
	v_lshlrev_b32_e32 v62, 16, v54
	v_lshlrev_b32_e32 v64, 16, v55
	v_lshlrev_b32_e32 v86, 16, v56
	v_lshlrev_b32_e32 v88, 16, v57
	v_lshlrev_b32_e32 v90, 16, v58
	v_lshlrev_b32_e32 v92, 16, v59
	v_mul_f32_e32 v51, v51, v51
	v_mul_f32_e32 v61, v61, v61
	v_mul_f32_e32 v63, v63, v63
	v_mul_f32_e32 v65, v65, v65
	v_mul_f32_e32 v87, v87, v87
	v_mul_f32_e32 v89, v89, v89
	v_mul_f32_e32 v91, v91, v91
	v_mul_f32_e32 v93, v93, v93
	v_fmac_f32_e32 v51, v50, v50
	v_fmac_f32_e32 v61, v60, v60
	v_fmac_f32_e32 v63, v62, v62
	v_fmac_f32_e32 v65, v64, v64
	v_fmac_f32_e32 v87, v86, v86
	v_fmac_f32_e32 v89, v88, v88
	v_fmac_f32_e32 v91, v90, v90
	v_fmac_f32_e32 v93, v92, v92
	v_add_f32_e32 v50, v51, v61
	v_add_f32_e32 v51, v63, v65
	v_add_f32_e32 v60, v87, v89
	v_add_f32_e32 v61, v91, v93
	v_add_f32_e32 v50, v50, v51
	v_add_f32_e32 v51, v60, v61
	v_add_f32_e32 v50, v50, v51
	ds_bpermute_b32 v51, v122, v50
	v_lshlrev_b64 v[60:61], 11, v[84:85]
	v_lshl_add_u64 v[60:61], s[2:3], 0, v[60:61]
	v_lshl_add_u64 v[60:61], v[148:149], 1, v[60:61]
	s_waitcnt vmcnt(0)
	global_store_dwordx4 v[60:61], v[52:55], off
	global_store_dwordx4 v[60:61], v[56:59], off offset:256
	s_waitcnt lgkmcnt(0)
	v_add_f32_e32 v50, v50, v51
	ds_bpermute_b32 v51, v123, v50
	s_and_saveexec_b64 s[4:5], vcc
	s_cbranch_execz .LBB0_630
	v_lshlrev_b64 v[52:53], 6, v[84:85]
	v_lshl_add_u64 v[52:53], s[8:9], 0, v[52:53]
	s_lshl_b32 s12, s34, 2
	v_lshl_add_u64 v[52:53], v[52:53], 0, s[12:13]
	s_waitcnt lgkmcnt(0)
	v_add_f32_e32 v50, v50, v51
	global_store_dword v[52:53], v50, off
.LBB0_630:
	s_or_b64 exec, exec, s[4:5]
	v_pk_add_f32 v[46:47], v[46:47], v[78:79]
	v_pk_add_f32 v[48:49], v[48:49], v[80:81]
	s_waitcnt lgkmcnt(0)
	v_pk_add_f32 v[50:51], v[44:45], v[76:77]
	v_pk_add_f32 v[44:45], v[42:43], v[74:75]
	v_cvt_pk_bf16_f32 v42, v46, v47
	v_cvt_pk_bf16_f32 v43, v48, v49
	v_pk_add_f32 v[38:39], v[38:39], v[70:71]
	v_and_b32_e32 v47, 0xffff0000, v42
	v_lshlrev_b32_e32 v46, 16, v42
	v_and_b32_e32 v49, 0xffff0000, v43
	v_mul_f32_e32 v47, v47, v47
	v_lshlrev_b32_e32 v48, 16, v43
	v_fmac_f32_e32 v47, v46, v46
	v_mul_f32_e32 v46, v49, v49
	v_cvt_pk_bf16_f32 v44, v44, v45
	v_cvt_pk_bf16_f32 v45, v50, v51
	v_fmac_f32_e32 v46, v48, v48
	v_and_b32_e32 v51, 0xffff0000, v44
	v_and_b32_e32 v53, 0xffff0000, v45
	v_lshlrev_b32_e32 v50, 16, v44
	v_lshlrev_b32_e32 v52, 16, v45
	v_add_f32_e32 v46, v47, v46
	v_mul_f32_e32 v47, v51, v51
	v_mul_f32_e32 v48, v53, v53
	v_fmac_f32_e32 v47, v50, v50
	v_fmac_f32_e32 v48, v52, v52
	v_add_f32_e32 v47, v47, v48
	v_pk_add_f32 v[34:35], v[34:35], v[66:67]
	v_add_f32_e32 v48, v46, v47
	v_pk_add_f32 v[40:41], v[40:41], v[72:73]
	v_pk_add_f32 v[46:47], v[36:37], v[68:69]
	v_cvt_pk_bf16_f32 v36, v38, v39
	v_cvt_pk_bf16_f32 v38, v34, v35
	v_cvt_pk_bf16_f32 v37, v40, v41
	s_nop 0
	v_and_b32_e32 v35, 0xffff0000, v36
	v_lshlrev_b32_e32 v34, 16, v36
	v_and_b32_e32 v41, 0xffff0000, v37
	v_mul_f32_e32 v35, v35, v35
	v_lshlrev_b32_e32 v40, 16, v37
	v_fmac_f32_e32 v35, v34, v34
	v_mul_f32_e32 v34, v41, v41
	v_cvt_pk_bf16_f32 v39, v46, v47
	v_and_b32_e32 v47, 0xffff0000, v38
	v_and_b32_e32 v50, 0xffff0000, v39
	v_fmac_f32_e32 v34, v40, v40
	v_lshlrev_b32_e32 v46, 16, v38
	v_lshlrev_b32_e32 v49, 16, v39
	v_add_f32_e32 v34, v35, v34
	v_mul_f32_e32 v35, v47, v47
	v_mul_f32_e32 v40, v50, v50
	v_fmac_f32_e32 v35, v46, v46
	v_fmac_f32_e32 v40, v49, v49
	v_add_f32_e32 v35, v35, v40
	v_add_f32_e32 v34, v34, v35
	v_add_f32_e32 v34, v48, v34
	ds_bpermute_b32 v35, v122, v34
	v_lshlrev_b64 v[40:41], 11, v[82:83]
	v_lshl_add_u64 v[40:41], s[2:3], 0, v[40:41]
	v_lshl_add_u64 v[40:41], v[148:149], 1, v[40:41]
	global_store_dwordx4 v[40:41], v[42:45], off
	global_store_dwordx4 v[40:41], v[36:39], off offset:256
	s_waitcnt lgkmcnt(0)
	v_add_f32_e32 v34, v34, v35
	ds_bpermute_b32 v35, v123, v34
	s_and_saveexec_b64 s[4:5], vcc
	s_cbranch_execz .LBB0_632
	v_lshlrev_b64 v[36:37], 6, v[82:83]
	v_lshl_add_u64 v[36:37], s[8:9], 0, v[36:37]
	s_lshl_b32 s12, s34, 2
	v_lshl_add_u64 v[36:37], v[36:37], 0, s[12:13]
	s_waitcnt lgkmcnt(0)
	v_add_f32_e32 v34, v34, v35
	global_store_dword v[36:37], v34, off
.LBB0_632:
	s_or_b64 exec, exec, s[4:5]
	v_readlane_b32 s80, v242, 21
	v_readlane_b32 s81, v242, 22
	v_add_u32_e32 v52, 0xa0, v150
	v_readlane_b32 s82, v242, 23
	v_readlane_b32 s83, v242, 24
	s_mov_b64 s[36:37], s[80:81]
	v_add_u32_e32 v34, 0xffffc0a0, v150
	v_ashrrev_i32_e32 v53, 31, v52
	v_cmp_gt_i32_e64 s[4:5], s45, v52
	s_mov_b64 s[38:39], s[82:83]
	v_mov_b32_e32 v38, s39
	s_waitcnt lgkmcnt(0)
	v_cndmask_b32_e64 v35, 0, v53, s[4:5]
	v_cndmask_b32_e64 v34, v34, v52, s[4:5]
	v_mov_b32_e32 v39, s37
	v_mov_b32_e32 v40, s38
	v_mov_b32_e32 v41, s36
	v_cndmask_b32_e64 v37, v38, v39, s[4:5]
	v_cndmask_b32_e64 v36, v40, v41, s[4:5]
	v_lshlrev_b64 v[34:35], 12, v[34:35]
	v_lshl_add_u64 v[34:35], v[36:37], 0, v[34:35]
	v_lshl_add_u64 v[34:35], v[34:35], 0, v[152:153]
	global_load_dwordx4 v[54:57], v[34:35], off
	global_load_dwordx4 v[58:61], v[34:35], off offset:16
	global_load_dwordx4 v[62:65], v[34:35], off offset:512
	global_load_dwordx4 v[66:69], v[34:35], off offset:528
	v_add_u32_e32 v50, 0xb0, v150
	v_add_u32_e32 v34, 0xffffc0b0, v150
	v_ashrrev_i32_e32 v51, 31, v50
	v_cmp_gt_i32_e64 s[4:5], s45, v50
	v_readlane_b32 s84, v242, 25
	v_readlane_b32 s85, v242, 26
	v_cndmask_b32_e64 v35, 0, v51, s[4:5]
	v_cndmask_b32_e64 v34, v34, v50, s[4:5]
	v_cndmask_b32_e64 v37, v38, v39, s[4:5]
	v_cndmask_b32_e64 v36, v40, v41, s[4:5]
	v_lshlrev_b64 v[34:35], 12, v[34:35]
	v_lshl_add_u64 v[34:35], v[36:37], 0, v[34:35]
	v_lshl_add_u64 v[38:39], v[34:35], 0, v[152:153]
	global_load_dwordx4 v[42:45], v[38:39], off offset:16
	global_load_dwordx4 v[46:49], v[38:39], off
	global_load_dwordx4 v[34:37], v[38:39], off offset:528
	s_nop 0
	global_load_dwordx4 v[38:41], v[38:39], off offset:512
	v_readlane_b32 s86, v242, 27
	v_readlane_b32 s87, v242, 28
	v_readlane_b32 s88, v242, 29
	v_readlane_b32 s89, v242, 30
	v_readlane_b32 s90, v242, 31
	v_readlane_b32 s91, v242, 32
	v_readlane_b32 s92, v242, 33
	v_readlane_b32 s93, v242, 34
	v_readlane_b32 s94, v242, 35
	v_readlane_b32 s95, v242, 36
	s_waitcnt vmcnt(7)
	v_pk_add_f32 v[32:33], v[32:33], v[56:57]
	v_pk_add_f32 v[30:31], v[30:31], v[54:55]
	s_waitcnt vmcnt(6)
	v_pk_add_f32 v[28:29], v[28:29], v[60:61]
	v_pk_add_f32 v[26:27], v[26:27], v[58:59]
	s_waitcnt vmcnt(5)
	v_pk_add_f32 v[54:55], v[24:25], v[64:65]
	v_pk_add_f32 v[24:25], v[22:23], v[62:63]
	s_waitcnt vmcnt(4)
	v_pk_add_f32 v[56:57], v[20:21], v[68:69]
	v_pk_add_f32 v[18:19], v[18:19], v[66:67]
	v_cvt_pk_bf16_f32 v20, v30, v31
	v_cvt_pk_bf16_f32 v21, v32, v33
	v_cvt_pk_bf16_f32 v22, v26, v27
	v_cvt_pk_bf16_f32 v23, v28, v29
	v_cvt_pk_bf16_f32 v24, v24, v25
	v_cvt_pk_bf16_f32 v25, v54, v55
	s_nop 0
	v_cvt_pk_bf16_f32 v26, v18, v19
	v_cvt_pk_bf16_f32 v27, v56, v57
	v_and_b32_e32 v19, 0xffff0000, v20
	v_and_b32_e32 v29, 0xffff0000, v21
	v_and_b32_e32 v31, 0xffff0000, v22
	v_and_b32_e32 v33, 0xffff0000, v23
	v_and_b32_e32 v55, 0xffff0000, v24
	v_and_b32_e32 v57, 0xffff0000, v25
	v_and_b32_e32 v59, 0xffff0000, v26
	v_and_b32_e32 v61, 0xffff0000, v27
	v_lshlrev_b32_e32 v18, 16, v20
	v_lshlrev_b32_e32 v28, 16, v21
	v_lshlrev_b32_e32 v30, 16, v22
	v_lshlrev_b32_e32 v32, 16, v23
	v_lshlrev_b32_e32 v54, 16, v24
	v_lshlrev_b32_e32 v56, 16, v25
	v_lshlrev_b32_e32 v58, 16, v26
	v_lshlrev_b32_e32 v60, 16, v27
	v_mul_f32_e32 v19, v19, v19
	v_mul_f32_e32 v29, v29, v29
	v_mul_f32_e32 v31, v31, v31
	v_mul_f32_e32 v33, v33, v33
	v_mul_f32_e32 v55, v55, v55
	v_mul_f32_e32 v57, v57, v57
	v_mul_f32_e32 v59, v59, v59
	v_mul_f32_e32 v61, v61, v61
	v_fmac_f32_e32 v19, v18, v18
	v_fmac_f32_e32 v29, v28, v28
	v_fmac_f32_e32 v31, v30, v30
	v_fmac_f32_e32 v33, v32, v32
	v_fmac_f32_e32 v55, v54, v54
	v_fmac_f32_e32 v57, v56, v56
	v_fmac_f32_e32 v59, v58, v58
	v_fmac_f32_e32 v61, v60, v60
	v_add_f32_e32 v18, v19, v29
	v_add_f32_e32 v19, v31, v33
	v_add_f32_e32 v28, v55, v57
	v_add_f32_e32 v29, v59, v61
	v_add_f32_e32 v18, v18, v19
	v_add_f32_e32 v19, v28, v29
	v_add_f32_e32 v18, v18, v19
	ds_bpermute_b32 v19, v122, v18
	v_lshlrev_b64 v[28:29], 11, v[52:53]
	v_lshl_add_u64 v[28:29], s[2:3], 0, v[28:29]
	v_lshl_add_u64 v[28:29], v[148:149], 1, v[28:29]
	s_waitcnt vmcnt(0)
	global_store_dwordx4 v[28:29], v[20:23], off
	global_store_dwordx4 v[28:29], v[24:27], off offset:256
	s_waitcnt lgkmcnt(0)
	v_add_f32_e32 v18, v18, v19
	ds_bpermute_b32 v19, v123, v18
	s_and_saveexec_b64 s[4:5], vcc
	s_cbranch_execz .LBB0_634
	v_lshlrev_b64 v[20:21], 6, v[52:53]
	v_lshl_add_u64 v[20:21], s[8:9], 0, v[20:21]
	s_lshl_b32 s12, s34, 2
	v_lshl_add_u64 v[20:21], v[20:21], 0, s[12:13]
	s_waitcnt lgkmcnt(0)
	v_add_f32_e32 v18, v18, v19
	global_store_dword v[20:21], v18, off
.LBB0_634:
	s_or_b64 exec, exec, s[4:5]
	v_pk_add_f32 v[14:15], v[14:15], v[46:47]
	v_pk_add_f32 v[16:17], v[16:17], v[48:49]
	s_waitcnt lgkmcnt(0)
	v_pk_add_f32 v[18:19], v[12:13], v[44:45]
	v_pk_add_f32 v[12:13], v[10:11], v[42:43]
	v_cvt_pk_bf16_f32 v10, v14, v15
	v_cvt_pk_bf16_f32 v11, v16, v17
	v_pk_add_f32 v[6:7], v[6:7], v[38:39]
	v_and_b32_e32 v15, 0xffff0000, v10
	v_lshlrev_b32_e32 v14, 16, v10
	v_and_b32_e32 v17, 0xffff0000, v11
	v_mul_f32_e32 v15, v15, v15
	v_lshlrev_b32_e32 v16, 16, v11
	v_fmac_f32_e32 v15, v14, v14
	v_mul_f32_e32 v14, v17, v17
	v_cvt_pk_bf16_f32 v12, v12, v13
	v_cvt_pk_bf16_f32 v13, v18, v19
	v_fmac_f32_e32 v14, v16, v16
	v_and_b32_e32 v19, 0xffff0000, v12
	v_and_b32_e32 v21, 0xffff0000, v13
	v_lshlrev_b32_e32 v18, 16, v12
	v_lshlrev_b32_e32 v20, 16, v13
	v_add_f32_e32 v14, v15, v14
	v_mul_f32_e32 v15, v19, v19
	v_mul_f32_e32 v16, v21, v21
	v_fmac_f32_e32 v15, v18, v18
	v_fmac_f32_e32 v16, v20, v20
	v_add_f32_e32 v15, v15, v16
	v_pk_add_f32 v[2:3], v[2:3], v[34:35]
	v_add_f32_e32 v16, v14, v15
	v_pk_add_f32 v[8:9], v[8:9], v[40:41]
	v_pk_add_f32 v[14:15], v[4:5], v[36:37]
	v_cvt_pk_bf16_f32 v4, v6, v7
	v_cvt_pk_bf16_f32 v6, v2, v3
	v_cvt_pk_bf16_f32 v5, v8, v9
	s_nop 0
	v_and_b32_e32 v3, 0xffff0000, v4
	v_lshlrev_b32_e32 v2, 16, v4
	v_and_b32_e32 v9, 0xffff0000, v5
	v_mul_f32_e32 v3, v3, v3
	v_lshlrev_b32_e32 v8, 16, v5
	v_fmac_f32_e32 v3, v2, v2
	v_mul_f32_e32 v2, v9, v9
	v_cvt_pk_bf16_f32 v7, v14, v15
	v_and_b32_e32 v15, 0xffff0000, v6
	v_and_b32_e32 v18, 0xffff0000, v7
	v_fmac_f32_e32 v2, v8, v8
	v_lshlrev_b32_e32 v14, 16, v6
	v_lshlrev_b32_e32 v17, 16, v7
	v_add_f32_e32 v2, v3, v2
	v_mul_f32_e32 v3, v15, v15
	v_mul_f32_e32 v8, v18, v18
	v_fmac_f32_e32 v3, v14, v14
	v_fmac_f32_e32 v8, v17, v17
	v_add_f32_e32 v3, v3, v8
	v_add_f32_e32 v2, v2, v3
	v_add_f32_e32 v2, v16, v2
	ds_bpermute_b32 v3, v122, v2
	v_lshlrev_b64 v[8:9], 11, v[50:51]
	v_lshl_add_u64 v[8:9], s[2:3], 0, v[8:9]
	v_lshl_add_u64 v[8:9], v[148:149], 1, v[8:9]
	global_store_dwordx4 v[8:9], v[10:13], off
	global_store_dwordx4 v[8:9], v[4:7], off offset:256
	s_waitcnt lgkmcnt(0)
	v_add_f32_e32 v2, v2, v3
	ds_bpermute_b32 v3, v123, v2
	s_and_saveexec_b64 s[4:5], vcc
	s_cbranch_execz .LBB0_609
	v_lshlrev_b64 v[4:5], 6, v[50:51]
	v_lshl_add_u64 v[4:5], s[8:9], 0, v[4:5]
	s_lshl_b32 s12, s34, 2
	v_lshl_add_u64 v[4:5], v[4:5], 0, s[12:13]
	s_waitcnt lgkmcnt(0)
	v_add_f32_e32 v2, v2, v3
	global_store_dword v[4:5], v2, off
	s_branch .LBB0_609
